# hand-pipelined LRU-prompt chunk loop (weights in registers, batched LDS, conv overlapped with scan, 2 barriers per chunk) on top of attnA + gates; all blocks padded to baseline addresses
# speedup vs baseline: 1.0171x; 1.0102x over previous
; #define LAS __attribute__((address_space(3)))
; __device__ __forceinline__ void lru_unit_p(const P2Ctx& C, int b, int n, int half) {
;     ...
;     { const int chg0 = n * 128 + half * 64 + ((tid0 >> 6) & 1) * 32 + (tid0 & 31); ba = a.in[I_BRGA][chg0] * LOG2E; bx = a.in[I_BRGX][chg0] * LOG2E; sp8 = 8.0f * LOG2E * log1pf(expf(-a.in[I_RGL][chg0])); }
;     ...
;     { const int cg0 = tid0 & 15, tt00 = (tid0 >> 4) * 4;
; #pragma unroll
;       for (int i = 0; i < 7; ++i) { const int ts = tt00 - 3 + i; rows[i] = ts >= 0 ? *(const u32x4*)(C.XB + (t0 + ts) * DM + n * 128 + cg0 * 8) : (u32x4){0u, 0u, 0u, 0u}; } }
;     for (int ck = 0; ck < 16; ++ck) {
;         int tid = tid0; asm volatile("" : "+v"(tid));
;         const int lane = tid & 63, wid = __builtin_amdgcn_readfirstlane(tid >> 6);
;         const int r32 = lane & 31, hi = lane >> 5, tkb = wid >> 1, chb = wid & 1;
;         const int chl = half * 64 + chb * 32 + r32;
;         const int cg = tid & 15, run = tid >> 4;
;         u32x4 rown[7];
;         if (ck + 1 < 16) { const int ttn = (ck + 1) * 128 + run * 4;
; #pragma unroll
;             for (int i = 0; i < 7; ++i) rown[i] = *(const u32x4*)(C.XB + (t0 + ttn - 3 + i) * DM + n * 128 + cg * 8); }
;         else {
; #pragma unroll
;             for (int i = 0; i < 7; ++i) rown[i] = (u32x4){0u, 0u, 0u, 0u}; }
;         bf16_t gg[16];
;         const size_t off0 = (t0 + ck * 128 + (tid >> 6) * 16) * DM + n * 128 + half * 64 + (tid & 63);
; #pragma unroll
;         for (int t = 0; t < 16; ++t) gg[t] = C.GG[off0 + (size_t)t * DM];
;         { float cw[4][8], cb8[8];
;           { const LAS float* cbp = CWL + 512 + cg * 8; const f32x4 c0 = *(const LAS f32x4*)cbp, c1 = *(const LAS f32x4*)(cbp + 4);
;             cb8[0] = c0[0]; cb8[1] = c0[1]; cb8[2] = c0[2]; cb8[3] = c0[3]; cb8[4] = c1[0]; cb8[5] = c1[1]; cb8[6] = c1[2]; cb8[7] = c1[3]; }
; #pragma unroll
;           for (int j = 0; j < 4; ++j) { const LAS float* cwp = CWL + j * 128 + cg * 8; const f32x4 c0 = *(const LAS f32x4*)cwp, c1 = *(const LAS f32x4*)(cwp + 4);
;               cw[j][0] = c0[0]; cw[j][1] = c0[1]; cw[j][2] = c0[2]; cw[j][3] = c0[3]; cw[j][4] = c1[0]; cw[j][5] = c1[1]; cw[j][6] = c1[2]; cw[j][7] = c1[3]; }
;           float x[7][8];
; #pragma unroll
;           for (int i = 0; i < 7; ++i) unpack8(rows[i], x[i]);
; #pragma unroll
;           for (int t = 0; t < 4; ++t) { float xc[8];
; #pragma unroll
.LBB0_539:
	s_or_b64 exec, exec, s[16:17]
	v_mul_f32_e32 v2, 0xbfb8aa3b, v35
	v_rndne_f32_e32 v32, v2
	v_sub_f32_e32 v33, v2, v32
	v_fma_f32 v2, v35, s97, -v2
	v_fmac_f32_e32 v2, 0xb2a5705f, v35
	v_add_f32_e32 v2, v33, v2
	v_exp_f32_e32 v2, v2
	v_cvt_i32_f32_e32 v32, v32
	v_cmp_nlt_f32_e32 vcc, s28, v35
	v_mul_f32_e32 v67, 0x3fb8aa3b, v34
	v_mul_f32_e32 v68, 0x3fb8aa3b, v36
	v_ldexp_f32 v2, v2, v32
	v_cndmask_b32_e32 v2, 0, v2, vcc
	v_cmp_ngt_f32_e32 vcc, s86, v35
	s_add_u32 s16, s10, -3
	s_mov_b32 s20, 0
	v_cndmask_b32_e32 v2, v210, v2, vcc
	v_add_f32_e32 v34, 1.0, v2
	v_add_f32_e32 v32, -1.0, v34
	v_sub_f32_e32 v33, v32, v34
	v_add_f32_e32 v33, 1.0, v33
	v_sub_f32_e32 v32, v2, v32
	v_add_f32_e32 v35, v32, v33
	v_frexp_mant_f32_e32 v36, v34
	v_cvt_f64_f32_e32 v[32:33], v34
	v_frexp_exp_i32_f64_e32 v32, v[32:33]
	v_cmp_gt_f32_e32 vcc, s35, v36
	s_addc_u32 s17, s11, -1
	s_or_b32 s9, s13, s81
	v_subbrev_co_u32_e32 v32, vcc, 0, v32, vcc
	v_sub_u32_e32 v33, 0, v32
	v_ldexp_f32 v34, v34, v33
	v_ldexp_f32 v33, v35, v33
	v_add_f32_e32 v35, -1.0, v34
	v_add_f32_e32 v38, 1.0, v34
	v_add_f32_e32 v36, 1.0, v35
	v_add_f32_e32 v39, -1.0, v38
	v_sub_f32_e32 v36, v34, v36
	v_sub_f32_e32 v34, v34, v39
	v_add_f32_e32 v36, v33, v36
	v_add_f32_e32 v33, v33, v34
	v_add_f32_e32 v34, v38, v33
	v_rcp_f32_e32 v39, v34
	v_add_f32_e32 v37, v35, v36
	v_sub_f32_e32 v35, v35, v37
	v_add_f32_e32 v35, v36, v35
	v_sub_f32_e32 v36, v38, v34
	v_add_f32_e32 v33, v33, v36
	v_mul_f32_e32 v36, v37, v39
	v_mul_f32_e32 v38, v34, v36
	v_fma_f32 v40, v36, v34, -v38
	v_fmac_f32_e32 v40, v36, v33
	v_add_f32_e32 v41, v38, v40
	v_sub_f32_e32 v42, v37, v41
	v_sub_f32_e32 v37, v37, v42
	v_sub_f32_e32 v38, v41, v38
	v_sub_f32_e32 v37, v37, v41
	v_add_f32_e32 v35, v35, v37
	v_sub_f32_e32 v37, v38, v40
	v_add_f32_e32 v35, v37, v35
	v_add_f32_e32 v37, v42, v35
	v_mul_f32_e32 v38, v39, v37
	v_mul_f32_e32 v40, v34, v38
	v_fma_f32 v34, v38, v34, -v40
	v_fmac_f32_e32 v34, v38, v33
	v_sub_f32_e32 v33, v42, v37
	v_add_f32_e32 v33, v35, v33
	v_add_f32_e32 v35, v40, v34
	v_sub_f32_e32 v41, v37, v35
	v_sub_f32_e32 v37, v37, v41
	v_sub_f32_e32 v40, v35, v40
	v_sub_f32_e32 v35, v37, v35
	v_add_f32_e32 v33, v33, v35
	v_sub_f32_e32 v34, v40, v34
	v_cvt_f32_i32_e32 v32, v32
	v_add_f32_e32 v33, v34, v33
	v_add_f32_e32 v34, v36, v38
	v_add_f32_e32 v33, v41, v33
	v_sub_f32_e32 v35, v34, v36
	v_mul_f32_e32 v33, v39, v33
	v_sub_f32_e32 v35, v38, v35
	v_add_f32_e32 v33, v35, v33
	v_mul_f32_e32 v38, 0x3f317218, v32
	v_add_f32_e32 v35, v34, v33
	v_fma_f32 v39, v32, s44, -v38
	v_mul_f32_e32 v36, v35, v35
	v_fmac_f32_e32 v39, 0xb102e308, v32
	v_sub_f32_e32 v32, v35, v34
	v_fmamk_f32 v37, v36, 0x3e9b6dac, v199
	v_sub_f32_e32 v32, v33, v32
	v_add_f32_e32 v33, v38, v39
	v_fmaak_f32 v37, v36, v37, 0x3f2aaada
	v_sub_f32_e32 v34, v33, v38
	v_ldexp_f32 v38, v35, 1
	v_mul_f32_e32 v35, v35, v36
	v_mul_f32_e32 v35, v35, v37
	v_add_f32_e32 v36, v38, v35
	v_sub_f32_e32 v37, v36, v38
	v_ldexp_f32 v32, v32, 1
	v_sub_f32_e32 v35, v35, v37
	v_add_f32_e32 v32, v32, v35
	v_add_f32_e32 v35, v36, v32
	v_sub_f32_e32 v36, v35, v36
	v_sub_f32_e32 v32, v32, v36
	v_add_f32_e32 v36, v33, v35
	v_sub_f32_e32 v37, v36, v33
	v_sub_f32_e32 v38, v36, v37
	v_sub_f32_e32 v34, v39, v34
	v_sub_f32_e32 v33, v33, v38
	v_sub_f32_e32 v35, v35, v37
	v_add_f32_e32 v33, v35, v33
	v_add_f32_e32 v35, v34, v32
	v_sub_f32_e32 v37, v35, v34
	v_sub_f32_e32 v38, v35, v37
	v_sub_f32_e32 v34, v34, v38
	v_sub_f32_e32 v32, v32, v37
	v_add_f32_e32 v33, v35, v33
	v_add_f32_e32 v32, v32, v34
	v_add_f32_e32 v34, v36, v33
	v_sub_f32_e32 v35, v34, v36
	v_sub_f32_e32 v33, v33, v35
	v_add_f32_e32 v32, v32, v33
	v_add_f32_e32 v32, v34, v32
	v_cmp_neq_f32_e32 vcc, s29, v2
	s_nop 1
	v_cndmask_b32_e32 v32, v210, v32, vcc
	v_cmp_lt_f32_e64 vcc, |v2|, s45
	s_nop 1
	v_cndmask_b32_e32 v2, v32, v2, vcc
	v_mul_f32_e32 v69, 0xc138aa3b, v2
	s_waitcnt vmcnt(0) lgkmcnt(0)
	s_lshl_b32 s9, s8, 11
	s_mov_b32 s20, 0
	s_lshl_b32 s10, s9, 11
	s_lshl_b32 s11, s81, 1
	s_add_i32 s10, s10, s11
	s_add_u32 s14, s43, s10
	s_addc_u32 s15, s38, 0
	s_sub_u32 s14, s14, 0x2000
	s_subb_u32 s15, s15, 0
	s_lshl_b32 s11, s13, 1
	s_add_i32 s10, s10, s11
	s_add_u32 s16, s64, s10
	s_addc_u32 s17, s65, 0
	s_add_u32 s18, s66, s10
	s_addc_u32 s19, s67, 0
	v_and_b32_e32 v48, 63, v196
	v_lshrrev_b32_e32 v49, 6, v196
	v_and_b32_e32 v50, 31, v196
	v_bfe_u32 v51, v196, 5, 1
	v_and_b32_e32 v52, 1, v49
	v_lshrrev_b32_e32 v53, 1, v49
	v_and_b32_e32 v54, 15, v196
	v_lshrrev_b32_e32 v55, 4, v196
	v_readfirstlane_b32 s21, v49
	v_lshlrev_b32_e32 v56, 13, v55
	v_lshl_add_u32 v56, v54, 4, v56
	v_add_u32_e32 v200, 0x1800, v56
	v_add_u32_e32 v201, 0x3000, v56
	v_lshlrev_b32_e32 v56, 15, v49
	v_lshl_add_u32 v202, v48, 1, v56
	v_lshlrev_b32_e32 v56, 5, v54
	v_add_u32_e32 v204, 0x23500, v56
	v_lshlrev_b32_e32 v56, 2, v55
	v_and_b32_e32 v57, 15, v56
	v_xor_b32_e32 v57, v57, v54
	v_lshlrev_b32_e32 v57, 4, v57
	v_lshl_add_u32 v192, v56, 8, v57
	v_lshlrev_b32_e32 v56, 2, v55
	v_or_b32_e32 v56, 1, v56
	v_and_b32_e32 v57, 15, v56
	v_xor_b32_e32 v57, v57, v54
	v_lshlrev_b32_e32 v57, 4, v57
	v_lshl_add_u32 v193, v56, 8, v57
	v_lshlrev_b32_e32 v56, 2, v55
	v_or_b32_e32 v56, 2, v56
	v_and_b32_e32 v57, 15, v56
	v_xor_b32_e32 v57, v57, v54
	v_lshlrev_b32_e32 v57, 4, v57
	v_lshl_add_u32 v194, v56, 8, v57
	v_lshlrev_b32_e32 v56, 2, v55
	v_or_b32_e32 v56, 3, v56
	v_and_b32_e32 v57, 15, v56
	v_xor_b32_e32 v57, v57, v54
	v_lshlrev_b32_e32 v57, 4, v57
	v_lshl_add_u32 v195, v56, 8, v57
	v_lshl_add_u32 v56, v53, 5, v50
	v_and_b32_e32 v57, 15, v56
	v_xor_b32_e32 v57, v57, v51
	v_lshlrev_b32_e32 v57, 4, v57
	v_lshl_add_u32 v174, v56, 8, v57
	v_xor_b32_e32 v175, 0x20, v174
	v_xor_b32_e32 v176, 0x40, v174
	v_xor_b32_e32 v177, 0x60, v174
	v_xor_b32_e32 v178, 0x80, v174
	v_xor_b32_e32 v179, 0xa0, v174
	v_xor_b32_e32 v180, 0xc0, v174
	v_xor_b32_e32 v181, 0xe0, v174
	v_lshl_add_u32 v56, v52, 5, v50
	v_and_b32_e32 v57, 15, v56
	v_xor_b32_e32 v57, v57, v51
	v_lshlrev_b32_e32 v57, 4, v57
	v_lshl_add_u32 v57, v56, 8, v57
	v_add_u32_e32 v57, 0x18000, v57
	ds_read_b128 v[70:73], v57
	ds_read_b128 v[102:105], v57 offset:16384
	v_xor_b32_e32 v58, 0x20, v57
	ds_read_b128 v[74:77], v58
	ds_read_b128 v[106:109], v58 offset:16384
	v_xor_b32_e32 v58, 0x40, v57
	ds_read_b128 v[78:81], v58
	ds_read_b128 v[110:113], v58 offset:16384
	v_xor_b32_e32 v58, 0x60, v57
	ds_read_b128 v[82:85], v58
	ds_read_b128 v[114:117], v58 offset:16384
	s_waitcnt lgkmcnt(0)
; #define LAS __attribute__((address_space(3)))
; __device__ __forceinline__ float bf2f(bf16_t v) { return __uint_as_float(((unsigned)v) << 16); }
; __device__ __forceinline__ float fexp2(float x) { return __builtin_amdgcn_exp2f(x); }
; __device__ __forceinline__ void lru_unit_p(const P2Ctx& C, int b, int n, int half) {
;     ...
;     { const int cg0 = tid0 & 15, tt00 = (tid0 >> 4) * 4;
; #pragma unroll
;       for (int i = 0; i < 7; ++i) { const int ts = tt00 - 3 + i; rows[i] = ts >= 0 ? *(const u32x4*)(C.XB + (t0 + ts) * DM + n * 128 + cg0 * 8) : (u32x4){0u, 0u, 0u, 0u}; } }
;     ...
;         { const int tokA = tkb * 32 + r32;
; #pragma unroll
;           for (int ks = 0; ks < 8; ++ks) { const bf16x8 xf = *(const LAS bf16x8*)(XC + tokA * 256 + (((2 * ks + hi) ^ (tokA & 15)) << 4));
;               const int wrow = chb * 32 + r32; const LAS unsigned char* wp = WL + wrow * 256 + (((2 * ks + hi) ^ (wrow & 15)) << 4);
;               da = MFMA32(xf, *(const LAS bf16x8*)wp, da); dx = MFMA32(xf, *(const LAS bf16x8*)(wp + 16384), dx); } }
; #pragma unroll
;         for (int r = 0; r < 16; ++r) { const int tokl = tkb * 32 + crow(r, hi);
;             const float xcv = bf2f(*(const LAS bf16_t*)(XC + tokl * 256 + (((chl >> 3) ^ (tokl & 15)) << 4) + (chl & 7) * 2));
;             const float rg = frcp(1.0f + fexp2(-(da[r] + ba))), ig = frcp(1.0f + fexp2(-(dx[r] + bx)));
;             const float av = fexp2(-sp8 * rg);
;             const float om = __builtin_fmaf(-av, av, 1.0f);
;             AA[tokl * 64 + chb * 32 + r32] = av; UU[tokl * 64 + chb * 32 + r32] = __builtin_amdgcn_sqrtf(om) * (ig * xcv);
;             if ((r & 3) == 3) __builtin_amdgcn_sched_barrier(0); }
;         __syncthreads();
;         { const int c = tid & 63, seg = tid >> 6;
;           float A = 1.f, B = 0.f;
; #pragma unroll
;           for (int t = 0; t < 16; ++t) { const int tok = seg * 16 + t; const float av = AA[tok * 64 + c], uv = UU[tok * 64 + c]; B = av * B + uv; A *= av; }
;           SEG[(seg * 64 + c) * 2] = A; SEG[(seg * 64 + c) * 2 + 1] = B;
;           __syncthreads();
;           float hin = CAR[c];
;           for (int s = 0; s < seg; ++s) hin = SEG[(s * 64 + c) * 2] * hin + SEG[(s * 64 + c) * 2 + 1];
;           float hv = hin;
; #pragma unroll
;           for (int t = 0; t < 16; ++t) { const int tok = seg * 16 + t; const float av = AA[tok * 64 + c], uv = UU[tok * 64 + c]; hv = av * hv + uv;
	v_xor_b32_e32 v58, 0x80, v57
	ds_read_b128 v[86:89], v58
	ds_read_b128 v[118:121], v58 offset:16384
	v_xor_b32_e32 v58, 0xa0, v57
	ds_read_b128 v[90:93], v58
	ds_read_b128 v[122:125], v58 offset:16384
	v_xor_b32_e32 v58, 0xc0, v57
	ds_read_b128 v[94:97], v58
	ds_read_b128 v[126:129], v58 offset:16384
	v_xor_b32_e32 v58, 0xe0, v57
	ds_read_b128 v[98:101], v58
	ds_read_b128 v[130:133], v58 offset:16384
	s_waitcnt lgkmcnt(0)
	v_lshl_add_u32 v56, v52, 5, v50
	v_add_u32_e32 v56, s13, v56
	v_lshrrev_b32_e32 v57, 3, v56
	v_lshlrev_b32_e32 v58, 2, v51
	v_xor_b32_e32 v57, v57, v58
	v_and_b32_e32 v59, 7, v56
	v_lshlrev_b32_e32 v59, 1, v59
	v_lshl_add_u32 v59, v57, 4, v59
	v_lshl_add_u32 v58, v53, 5, v58
	v_lshl_add_u32 v59, v58, 8, v59
	v_xor_b32_e32 v182, 0x0, v59
	v_xor_b32_e32 v183, 0x10, v59
	v_xor_b32_e32 v184, 0x20, v59
	v_xor_b32_e32 v185, 0x30, v59
	v_xor_b32_e32 v186, 0x80, v59
	v_xor_b32_e32 v187, 0x90, v59
	v_xor_b32_e32 v188, 0xa0, v59
	v_xor_b32_e32 v189, 0xb0, v59
	v_lshl_add_u32 v56, v52, 5, v50
	v_lshlrev_b32_e32 v56, 2, v56
	v_lshl_add_u32 v56, v58, 8, v56
	v_add_u32_e32 v190, 0x8000, v56
	v_lshlrev_b32_e32 v56, 12, v49
	v_lshl_add_u32 v56, v48, 2, v56
	v_add_u32_e32 v191, 0x8000, v56
	v_lshl_add_u32 v56, v49, 6, v48
	v_lshlrev_b32_e32 v56, 3, v56
	v_add_u32_e32 v197, 0x22400, v56
	v_lshlrev_b32_e32 v56, 3, v48
	v_add_u32_e32 v198, 0x22400, v56
	v_lshlrev_b32_e32 v56, 2, v48
	v_add_u32_e32 v203, 0x23400, v56
	s_mov_b32 s22, 0
	s_min_u32 s12, s22, 15
	s_lshl_b32 s12, s12, 18
	s_add_u32 s10, s14, s12
	s_addc_u32 s11, s15, 0
	global_load_dwordx4 v[4:7], v200, s[10:11] offset:-4096
	global_load_dwordx4 v[8:11], v200, s[10:11] offset:-2048
	global_load_dwordx4 v[12:15], v200, s[10:11] offset:0
	global_load_dwordx4 v[16:19], v200, s[10:11] offset:2048
	global_load_dwordx4 v[20:23], v201, s[10:11] offset:-2048
	global_load_dwordx4 v[24:27], v201, s[10:11] offset:0
	global_load_dwordx4 v[28:31], v201, s[10:11] offset:2048
	s_mov_b32 s20, -1
	s_waitcnt vmcnt(0) lgkmcnt(0)
	v_cmp_gt_u32_e32 vcc, 16, v196
	s_and_saveexec_b64 s[10:11], vcc
	s_cbranch_execz .LlP_nozero_1
	v_mov_b32_e32 v4, 0
	v_mov_b32_e32 v5, 0
	v_mov_b32_e32 v6, 0
	v_mov_b32_e32 v7, 0
	v_mov_b32_e32 v8, 0
	v_mov_b32_e32 v9, 0
	v_mov_b32_e32 v10, 0
	v_mov_b32_e32 v11, 0
	v_mov_b32_e32 v12, 0
	v_mov_b32_e32 v13, 0
	v_mov_b32_e32 v14, 0
	v_mov_b32_e32 v15, 0
.LlP_nozero_1:
	s_or_b64 exec, exec, s[10:11]
	s_branch .LlP_conv
	s_nop 0
	s_nop 0
	s_nop 0
	s_nop 0
	s_nop 0
	s_nop 0
	s_nop 0
	s_nop 0
	s_nop 0
	s_nop 0
	s_nop 0
	s_nop 0
	s_nop 0
	s_nop 0
	s_nop 0
	s_nop 0
	s_nop 0
	s_nop 0
	s_nop 0
	s_nop 0
	s_nop 0
	s_nop 0
	s_nop 0
	s_nop 0
	s_nop 0
	s_nop 0
	s_nop 0
	s_nop 0
	s_nop 0
	s_nop 0
	s_nop 0
	s_nop 0
	s_nop 0
	s_nop 0
	s_nop 0
	s_nop 0
	s_nop 0
	s_nop 0
	s_nop 0
	s_nop 0
	s_nop 0
	s_nop 0
	s_nop 0
	s_nop 0
	s_nop 0
	s_nop 0
	s_nop 0
	s_nop 0
	s_nop 0
	s_nop 0
	s_nop 0
	s_nop 0
	s_nop 0
	s_nop 0
	s_nop 0
	s_nop 0
	s_nop 0
	s_nop 0
	s_nop 0
	s_nop 0
	s_nop 0
	s_nop 0
	s_nop 0
	s_nop 0
	s_nop 0
	s_nop 0
	s_nop 0
	s_nop 0
	s_nop 0
	s_nop 0
	s_nop 0
	s_nop 0
	s_nop 0
	s_nop 0
	s_nop 0
	s_nop 0
	s_nop 0
	s_nop 0
	s_nop 0
	s_nop 0
	s_nop 0
	s_nop 0
	s_nop 0
	s_nop 0
	s_nop 0
	s_nop 0
	s_nop 0
	s_nop 0
	s_nop 0
	s_nop 0
	s_nop 0
	s_nop 0
	s_nop 0
	s_nop 0
	s_nop 0
	s_nop 0
	s_nop 0
	s_nop 0
	s_nop 0
	s_nop 0
	s_nop 0
	s_nop 0
	s_nop 0
	s_nop 0
	s_nop 0
	s_nop 0
	s_nop 0
	s_nop 0
	s_nop 0
	s_nop 0
	s_nop 0
	s_nop 0
	s_nop 0
	s_nop 0
	s_nop 0
	s_nop 0
	s_nop 0
	s_nop 0
	s_nop 0
	s_nop 0
	s_nop 0
	s_nop 0
	s_nop 0
	s_nop 0
	s_nop 0
	s_nop 0
	s_nop 0
	s_nop 0
	s_nop 0
	s_nop 0
	s_nop 0
	s_nop 0
	s_nop 0
	s_nop 0
	s_nop 0
	s_nop 0
	s_nop 0
	s_nop 0
	s_nop 0
	s_nop 0
	s_nop 0
	s_nop 0
	s_nop 0
	s_nop 0
	s_nop 0
	s_nop 0
	s_nop 0
	s_nop 0
	s_nop 0
	s_nop 0
	s_nop 0
	s_nop 0
	s_nop 0
	s_nop 0
	s_nop 0
	s_nop 0
	s_nop 0
	s_nop 0
	s_nop 0
	s_nop 0
	s_nop 0
	s_nop 0
	s_nop 0
	s_nop 0
	s_nop 0
	s_nop 0
	s_nop 0
	s_nop 0
	s_nop 0
	s_nop 0
	s_nop 0
	s_nop 0
	s_nop 0
	s_nop 0
	s_nop 0
	s_nop 0
	s_nop 0
	s_nop 0
	s_nop 0
	s_nop 0
	s_nop 0
	s_nop 0
	s_nop 0
	s_nop 0
	s_nop 0
	s_nop 0
	s_nop 0
	s_nop 0
	s_nop 0
	s_nop 0
	s_nop 0
	s_nop 0
	s_nop 0
	s_nop 0
	s_nop 0
	s_nop 0
	s_nop 0
	s_nop 0
	s_nop 0
	s_nop 0
	s_nop 0
	s_nop 0
	s_nop 0
	s_nop 0
	s_nop 0
	s_nop 0
	s_nop 0
	s_nop 0
	s_nop 0
	s_nop 0
	s_nop 0
	s_nop 0
	s_nop 0
	s_nop 0
	s_nop 0
	s_nop 0
	s_nop 0
	s_nop 0
	s_nop 0
	s_nop 0
	s_nop 0
	s_nop 0
	s_nop 0
	s_nop 0
	s_nop 0
	s_nop 0
	s_nop 0
	s_nop 0
	s_nop 0
	s_nop 0
	s_nop 0
	s_nop 0
	s_nop 0
	s_nop 0
	s_nop 0
	s_nop 0
	s_nop 0
	s_nop 0
	s_nop 0
	s_nop 0
	s_nop 0
	s_nop 0
	s_nop 0
	s_nop 0
	s_nop 0
	s_nop 0
	s_nop 0
	s_nop 0
	s_nop 0
	s_nop 0
	s_nop 0
	s_nop 0
	s_nop 0
	s_nop 0
	s_nop 0
	s_nop 0
	s_nop 0
	s_nop 0
	s_nop 0
	s_nop 0
	s_nop 0
	s_nop 0
	s_nop 0
	s_nop 0
	s_nop 0
	s_nop 0
	s_nop 0
	s_nop 0
	s_nop 0
	s_nop 0
	s_nop 0
	s_nop 0
	s_nop 0
; #define LAS __attribute__((address_space(3)))
; __device__ __forceinline__ float bf2f(bf16_t v) { return __uint_as_float(((unsigned)v) << 16); }
; __device__ __forceinline__ float fexp2(float x) { return __builtin_amdgcn_exp2f(x); }
; __device__ __forceinline__ float frcp(float x) { return __builtin_amdgcn_rcpf(x); }
; __device__ __forceinline__ int crow(int r, int hi) { return (r & 3) + 8 * (r >> 2) + 4 * hi; }
; #define MFMA32(a, b, c) __builtin_amdgcn_mfma_f32_32x32x16_bf16((a), (b), (c), 0, 0, 0)
; __device__ __forceinline__ void lru_unit_p(const P2Ctx& C, int b, int n, int half) {
;     ...
;         { const int tokA = tkb * 32 + r32;
; #pragma unroll
;           for (int ks = 0; ks < 8; ++ks) { const bf16x8 xf = *(const LAS bf16x8*)(XC + tokA * 256 + (((2 * ks + hi) ^ (tokA & 15)) << 4));
;               const int wrow = chb * 32 + r32; const LAS unsigned char* wp = WL + wrow * 256 + (((2 * ks + hi) ^ (wrow & 15)) << 4);
;               da = MFMA32(xf, *(const LAS bf16x8*)wp, da); dx = MFMA32(xf, *(const LAS bf16x8*)(wp + 16384), dx); } }
; #pragma unroll
;         for (int r = 0; r < 16; ++r) { const int tokl = tkb * 32 + crow(r, hi);
;             const float xcv = bf2f(*(const LAS bf16_t*)(XC + tokl * 256 + (((chl >> 3) ^ (tokl & 15)) << 4) + (chl & 7) * 2));
;             const float rg = frcp(1.0f + fexp2(-(da[r] + ba))), ig = frcp(1.0f + fexp2(-(dx[r] + bx)));
;             const float av = fexp2(-sp8 * rg);
;             const float om = __builtin_fmaf(-av, av, 1.0f);
;             AA[tokl * 64 + chb * 32 + r32] = av; UU[tokl * 64 + chb * 32 + r32] = __builtin_amdgcn_sqrtf(om) * (ig * xcv);
;             if ((r & 3) == 3) __builtin_amdgcn_sched_barrier(0); }
.LlP_loop:
	ds_read_b128 v[240:243], v174
	ds_read_b128 v[244:247], v175
	ds_read_b128 v[248:251], v176
	s_waitcnt lgkmcnt(2)
	v_mfma_f32_32x32x16_bf16 v[220:235], v[240:243], v[70:73], 0
	v_mfma_f32_32x32x16_bf16 v[134:149], v[240:243], v[102:105], 0
	ds_read_b128 v[240:243], v177
	ds_read_u16 v150, v182 offset:0
	ds_read_u16 v151, v183 offset:256
	s_waitcnt lgkmcnt(4)
	v_mfma_f32_32x32x16_bf16 v[220:235], v[244:247], v[74:77], v[220:235]
	v_mfma_f32_32x32x16_bf16 v[134:149], v[244:247], v[106:109], v[134:149]
	ds_read_b128 v[244:247], v178
	ds_read_u16 v152, v184 offset:512
	ds_read_u16 v153, v185 offset:768
	s_waitcnt lgkmcnt(6)
	v_mfma_f32_32x32x16_bf16 v[220:235], v[248:251], v[78:81], v[220:235]
	v_mfma_f32_32x32x16_bf16 v[134:149], v[248:251], v[110:113], v[134:149]
	ds_read_b128 v[248:251], v179
	ds_read_u16 v154, v186 offset:2048
	ds_read_u16 v155, v187 offset:2304
	s_waitcnt lgkmcnt(8)
	v_mfma_f32_32x32x16_bf16 v[220:235], v[240:243], v[82:85], v[220:235]
	v_mfma_f32_32x32x16_bf16 v[134:149], v[240:243], v[114:117], v[134:149]
	ds_read_b128 v[240:243], v180
	ds_read_u16 v156, v188 offset:2560
	ds_read_u16 v157, v189 offset:2816
	s_waitcnt lgkmcnt(8)
	v_mfma_f32_32x32x16_bf16 v[220:235], v[244:247], v[86:89], v[220:235]
	v_mfma_f32_32x32x16_bf16 v[134:149], v[244:247], v[118:121], v[134:149]
	ds_read_b128 v[244:247], v181
	ds_read_u16 v158, v182 offset:4096
	ds_read_u16 v159, v183 offset:4352
	s_waitcnt lgkmcnt(8)
	v_mfma_f32_32x32x16_bf16 v[220:235], v[248:251], v[90:93], v[220:235]
	v_mfma_f32_32x32x16_bf16 v[134:149], v[248:251], v[122:125], v[134:149]
	ds_read_u16 v160, v184 offset:4608
	ds_read_u16 v161, v185 offset:4864
	s_waitcnt lgkmcnt(7)
	v_mfma_f32_32x32x16_bf16 v[220:235], v[240:243], v[94:97], v[220:235]
	v_mfma_f32_32x32x16_bf16 v[134:149], v[240:243], v[126:129], v[134:149]
	ds_read_u16 v162, v186 offset:6144
	ds_read_u16 v163, v187 offset:6400
	s_waitcnt lgkmcnt(6)
	v_mfma_f32_32x32x16_bf16 v[220:235], v[244:247], v[98:101], v[220:235]
	v_mfma_f32_32x32x16_bf16 v[134:149], v[244:247], v[130:133], v[134:149]
	ds_read_u16 v164, v188 offset:6656
	ds_read_u16 v165, v189 offset:6912
	s_waitcnt lgkmcnt(0)
	s_nop 7
	s_nop 3
	v_add_f32_e32 v48, v67, v220
	v_add_f32_e32 v52, v68, v134
	v_add_f32_e32 v49, v67, v221
	v_add_f32_e32 v53, v68, v135
	v_add_f32_e32 v50, v67, v222
	v_add_f32_e32 v54, v68, v136
	v_add_f32_e32 v51, v67, v223
	v_add_f32_e32 v55, v68, v137
	v_exp_f32_e64 v48, -v48
	v_exp_f32_e64 v52, -v52
	v_exp_f32_e64 v49, -v49
	v_exp_f32_e64 v53, -v53
	v_exp_f32_e64 v50, -v50
	v_exp_f32_e64 v54, -v54
	v_exp_f32_e64 v51, -v51
	v_exp_f32_e64 v55, -v55
	v_lshlrev_b32_e32 v56, 16, v150
	v_lshlrev_b32_e32 v57, 16, v151
	v_lshlrev_b32_e32 v58, 16, v152
	v_lshlrev_b32_e32 v59, 16, v153
	v_add_f32_e32 v48, 1.0, v48
	v_add_f32_e32 v52, 1.0, v52
	v_add_f32_e32 v49, 1.0, v49
	v_add_f32_e32 v53, 1.0, v53
	v_add_f32_e32 v50, 1.0, v50
	v_add_f32_e32 v54, 1.0, v54
	v_add_f32_e32 v51, 1.0, v51
	v_add_f32_e32 v55, 1.0, v55
	v_rcp_f32_e32 v48, v48
	v_rcp_f32_e32 v52, v52
	v_rcp_f32_e32 v49, v49
	v_rcp_f32_e32 v53, v53
	v_rcp_f32_e32 v50, v50
	v_rcp_f32_e32 v54, v54
	v_rcp_f32_e32 v51, v51
	v_rcp_f32_e32 v55, v55
	s_nop 0
	v_mul_f32_e32 v48, v69, v48
	v_mul_f32_e32 v56, v52, v56
	v_mul_f32_e32 v49, v69, v49
	v_mul_f32_e32 v57, v53, v57
	v_mul_f32_e32 v50, v69, v50
	v_mul_f32_e32 v58, v54, v58
	v_mul_f32_e32 v51, v69, v51
	v_mul_f32_e32 v59, v55, v59
	v_exp_f32_e32 v48, v48
	v_exp_f32_e32 v49, v49
	v_exp_f32_e32 v50, v50
	v_exp_f32_e32 v51, v51
	s_nop 0
	v_fma_f32 v60, -v48, v48, 1.0
	v_fma_f32 v61, -v49, v49, 1.0
	v_fma_f32 v62, -v50, v50, 1.0
	v_fma_f32 v63, -v51, v51, 1.0
	v_sqrt_f32_e32 v60, v60
	v_sqrt_f32_e32 v61, v61
	v_sqrt_f32_e32 v62, v62
	v_sqrt_f32_e32 v63, v63
	s_nop 0
	v_mul_f32_e32 v56, v60, v56
	ds_write_b32 v190, v48 offset:0
	ds_write_b32 v190, v56 offset:32768
	v_mul_f32_e32 v57, v61, v57
	ds_write_b32 v190, v49 offset:256
	ds_write_b32 v190, v57 offset:33024
	v_mul_f32_e32 v58, v62, v58
	ds_write_b32 v190, v50 offset:512
	ds_write_b32 v190, v58 offset:33280
	v_mul_f32_e32 v59, v63, v59
	ds_write_b32 v190, v51 offset:768
	ds_write_b32 v190, v59 offset:33536
	s_waitcnt lgkmcnt(4)
	v_add_f32_e32 v48, v67, v224
	v_add_f32_e32 v52, v68, v138
	v_add_f32_e32 v49, v67, v225
	v_add_f32_e32 v53, v68, v139
	v_add_f32_e32 v50, v67, v226
	v_add_f32_e32 v54, v68, v140
	v_add_f32_e32 v51, v67, v227
	v_add_f32_e32 v55, v68, v141
	v_exp_f32_e64 v48, -v48
	v_exp_f32_e64 v52, -v52
	v_exp_f32_e64 v49, -v49
	v_exp_f32_e64 v53, -v53
	v_exp_f32_e64 v50, -v50
	v_exp_f32_e64 v54, -v54
	v_exp_f32_e64 v51, -v51
	v_exp_f32_e64 v55, -v55
	v_lshlrev_b32_e32 v56, 16, v154
	v_lshlrev_b32_e32 v57, 16, v155
	v_lshlrev_b32_e32 v58, 16, v156
	v_lshlrev_b32_e32 v59, 16, v157
	v_add_f32_e32 v48, 1.0, v48
	v_add_f32_e32 v52, 1.0, v52
	v_add_f32_e32 v49, 1.0, v49
	v_add_f32_e32 v53, 1.0, v53
	v_add_f32_e32 v50, 1.0, v50
	v_add_f32_e32 v54, 1.0, v54
	v_add_f32_e32 v51, 1.0, v51
	v_add_f32_e32 v55, 1.0, v55
	v_rcp_f32_e32 v48, v48
	v_rcp_f32_e32 v52, v52
	v_rcp_f32_e32 v49, v49
	v_rcp_f32_e32 v53, v53
	v_rcp_f32_e32 v50, v50
	v_rcp_f32_e32 v54, v54
	v_rcp_f32_e32 v51, v51
	v_rcp_f32_e32 v55, v55
	s_nop 0
	v_mul_f32_e32 v48, v69, v48
	v_mul_f32_e32 v56, v52, v56
	v_mul_f32_e32 v49, v69, v49
	v_mul_f32_e32 v57, v53, v57
	v_mul_f32_e32 v50, v69, v50
	v_mul_f32_e32 v58, v54, v58
	v_mul_f32_e32 v51, v69, v51
	v_mul_f32_e32 v59, v55, v59
	v_exp_f32_e32 v48, v48
	v_exp_f32_e32 v49, v49
	v_exp_f32_e32 v50, v50
	v_exp_f32_e32 v51, v51
	s_nop 0
	v_fma_f32 v60, -v48, v48, 1.0
	v_fma_f32 v61, -v49, v49, 1.0
	v_fma_f32 v62, -v50, v50, 1.0
	v_fma_f32 v63, -v51, v51, 1.0
	v_sqrt_f32_e32 v60, v60
	v_sqrt_f32_e32 v61, v61
	v_sqrt_f32_e32 v62, v62
	v_sqrt_f32_e32 v63, v63
	s_nop 0
	v_mul_f32_e32 v56, v60, v56
	ds_write_b32 v190, v48 offset:2048
	ds_write_b32 v190, v56 offset:34816
	v_mul_f32_e32 v57, v61, v57
	ds_write_b32 v190, v49 offset:2304
	ds_write_b32 v190, v57 offset:35072
	v_mul_f32_e32 v58, v62, v58
	ds_write_b32 v190, v50 offset:2560
	ds_write_b32 v190, v58 offset:35328
	v_mul_f32_e32 v59, v63, v59
	ds_write_b32 v190, v51 offset:2816
	ds_write_b32 v190, v59 offset:35584
	s_waitcnt lgkmcnt(4)
; #define LAS __attribute__((address_space(3)))
; __device__ __forceinline__ float bf2f(bf16_t v) { return __uint_as_float(((unsigned)v) << 16); }
; __device__ __forceinline__ float fexp2(float x) { return __builtin_amdgcn_exp2f(x); }
; __device__ __forceinline__ float frcp(float x) { return __builtin_amdgcn_rcpf(x); }
; __device__ __forceinline__ int crow(int r, int hi) { return (r & 3) + 8 * (r >> 2) + 4 * hi; }
; __device__ __forceinline__ void lru_unit_p(const P2Ctx& C, int b, int n, int half) {
;     ...
;         for (int r = 0; r < 16; ++r) { const int tokl = tkb * 32 + crow(r, hi);
;             const float xcv = bf2f(*(const LAS bf16_t*)(XC + tokl * 256 + (((chl >> 3) ^ (tokl & 15)) << 4) + (chl & 7) * 2));
;             const float rg = frcp(1.0f + fexp2(-(da[r] + ba))), ig = frcp(1.0f + fexp2(-(dx[r] + bx)));
;             const float av = fexp2(-sp8 * rg);
;             const float om = __builtin_fmaf(-av, av, 1.0f);
;             AA[tokl * 64 + chb * 32 + r32] = av; UU[tokl * 64 + chb * 32 + r32] = __builtin_amdgcn_sqrtf(om) * (ig * xcv);
;             if ((r & 3) == 3) __builtin_amdgcn_sched_barrier(0); }
;         __syncthreads();
;         { const int c = tid & 63, seg = tid >> 6;
;           float A = 1.f, B = 0.f;
; #pragma unroll
;           for (int t = 0; t < 16; ++t) { const int tok = seg * 16 + t; const float av = AA[tok * 64 + c], uv = UU[tok * 64 + c]; B = av * B + uv; A *= av; }
;           SEG[(seg * 64 + c) * 2] = A; SEG[(seg * 64 + c) * 2 + 1] = B;
	v_add_f32_e32 v48, v67, v228
	v_add_f32_e32 v52, v68, v142
	v_add_f32_e32 v49, v67, v229
	v_add_f32_e32 v53, v68, v143
	v_add_f32_e32 v50, v67, v230
	v_add_f32_e32 v54, v68, v144
	v_add_f32_e32 v51, v67, v231
	v_add_f32_e32 v55, v68, v145
	v_exp_f32_e64 v48, -v48
	v_exp_f32_e64 v52, -v52
	v_exp_f32_e64 v49, -v49
	v_exp_f32_e64 v53, -v53
	v_exp_f32_e64 v50, -v50
	v_exp_f32_e64 v54, -v54
	v_exp_f32_e64 v51, -v51
	v_exp_f32_e64 v55, -v55
	v_lshlrev_b32_e32 v56, 16, v158
	v_lshlrev_b32_e32 v57, 16, v159
	v_lshlrev_b32_e32 v58, 16, v160
	v_lshlrev_b32_e32 v59, 16, v161
	v_add_f32_e32 v48, 1.0, v48
	v_add_f32_e32 v52, 1.0, v52
	v_add_f32_e32 v49, 1.0, v49
	v_add_f32_e32 v53, 1.0, v53
	v_add_f32_e32 v50, 1.0, v50
	v_add_f32_e32 v54, 1.0, v54
	v_add_f32_e32 v51, 1.0, v51
	v_add_f32_e32 v55, 1.0, v55
	v_rcp_f32_e32 v48, v48
	v_rcp_f32_e32 v52, v52
	v_rcp_f32_e32 v49, v49
	v_rcp_f32_e32 v53, v53
	v_rcp_f32_e32 v50, v50
	v_rcp_f32_e32 v54, v54
	v_rcp_f32_e32 v51, v51
	v_rcp_f32_e32 v55, v55
	s_nop 0
	v_mul_f32_e32 v48, v69, v48
	v_mul_f32_e32 v56, v52, v56
	v_mul_f32_e32 v49, v69, v49
	v_mul_f32_e32 v57, v53, v57
	v_mul_f32_e32 v50, v69, v50
	v_mul_f32_e32 v58, v54, v58
	v_mul_f32_e32 v51, v69, v51
	v_mul_f32_e32 v59, v55, v59
	v_exp_f32_e32 v48, v48
	v_exp_f32_e32 v49, v49
	v_exp_f32_e32 v50, v50
	v_exp_f32_e32 v51, v51
	s_nop 0
	v_fma_f32 v60, -v48, v48, 1.0
	v_fma_f32 v61, -v49, v49, 1.0
	v_fma_f32 v62, -v50, v50, 1.0
	v_fma_f32 v63, -v51, v51, 1.0
	v_sqrt_f32_e32 v60, v60
	v_sqrt_f32_e32 v61, v61
	v_sqrt_f32_e32 v62, v62
	v_sqrt_f32_e32 v63, v63
	s_nop 0
	v_mul_f32_e32 v56, v60, v56
	ds_write_b32 v190, v48 offset:4096
	ds_write_b32 v190, v56 offset:36864
	v_mul_f32_e32 v57, v61, v57
	ds_write_b32 v190, v49 offset:4352
	ds_write_b32 v190, v57 offset:37120
	v_mul_f32_e32 v58, v62, v58
	ds_write_b32 v190, v50 offset:4608
	ds_write_b32 v190, v58 offset:37376
	v_mul_f32_e32 v59, v63, v59
	ds_write_b32 v190, v51 offset:4864
	ds_write_b32 v190, v59 offset:37632
	s_waitcnt lgkmcnt(4)
	v_add_f32_e32 v48, v67, v232
	v_add_f32_e32 v52, v68, v146
	v_add_f32_e32 v49, v67, v233
	v_add_f32_e32 v53, v68, v147
	v_add_f32_e32 v50, v67, v234
	v_add_f32_e32 v54, v68, v148
	v_add_f32_e32 v51, v67, v235
	v_add_f32_e32 v55, v68, v149
	v_exp_f32_e64 v48, -v48
	v_exp_f32_e64 v52, -v52
	v_exp_f32_e64 v49, -v49
	v_exp_f32_e64 v53, -v53
	v_exp_f32_e64 v50, -v50
	v_exp_f32_e64 v54, -v54
	v_exp_f32_e64 v51, -v51
	v_exp_f32_e64 v55, -v55
	v_lshlrev_b32_e32 v56, 16, v162
	v_lshlrev_b32_e32 v57, 16, v163
	v_lshlrev_b32_e32 v58, 16, v164
	v_lshlrev_b32_e32 v59, 16, v165
	v_add_f32_e32 v48, 1.0, v48
	v_add_f32_e32 v52, 1.0, v52
	v_add_f32_e32 v49, 1.0, v49
	v_add_f32_e32 v53, 1.0, v53
	v_add_f32_e32 v50, 1.0, v50
	v_add_f32_e32 v54, 1.0, v54
	v_add_f32_e32 v51, 1.0, v51
	v_add_f32_e32 v55, 1.0, v55
	v_rcp_f32_e32 v48, v48
	v_rcp_f32_e32 v52, v52
	v_rcp_f32_e32 v49, v49
	v_rcp_f32_e32 v53, v53
	v_rcp_f32_e32 v50, v50
	v_rcp_f32_e32 v54, v54
	v_rcp_f32_e32 v51, v51
	v_rcp_f32_e32 v55, v55
	s_nop 0
	v_mul_f32_e32 v48, v69, v48
	v_mul_f32_e32 v56, v52, v56
	v_mul_f32_e32 v49, v69, v49
	v_mul_f32_e32 v57, v53, v57
	v_mul_f32_e32 v50, v69, v50
	v_mul_f32_e32 v58, v54, v58
	v_mul_f32_e32 v51, v69, v51
	v_mul_f32_e32 v59, v55, v59
	v_exp_f32_e32 v48, v48
	v_exp_f32_e32 v49, v49
	v_exp_f32_e32 v50, v50
	v_exp_f32_e32 v51, v51
	s_nop 0
	v_fma_f32 v60, -v48, v48, 1.0
	v_fma_f32 v61, -v49, v49, 1.0
	v_fma_f32 v62, -v50, v50, 1.0
	v_fma_f32 v63, -v51, v51, 1.0
	v_sqrt_f32_e32 v60, v60
	v_sqrt_f32_e32 v61, v61
	v_sqrt_f32_e32 v62, v62
	v_sqrt_f32_e32 v63, v63
	s_nop 0
	v_mul_f32_e32 v56, v60, v56
	ds_write_b32 v190, v48 offset:6144
	ds_write_b32 v190, v56 offset:38912
	v_mul_f32_e32 v57, v61, v57
	ds_write_b32 v190, v49 offset:6400
	ds_write_b32 v190, v57 offset:39168
	v_mul_f32_e32 v58, v62, v58
	ds_write_b32 v190, v50 offset:6656
	ds_write_b32 v190, v58 offset:39424
	v_mul_f32_e32 v59, v63, v59
	ds_write_b32 v190, v51 offset:6912
	ds_write_b32 v190, v59 offset:39680
	s_waitcnt lgkmcnt(0)
	s_waitcnt lgkmcnt(0)
	s_barrier
	ds_read_b32 v134, v191 offset:0
	ds_read_b32 v135, v191 offset:256
	ds_read_b32 v136, v191 offset:512
	ds_read_b32 v137, v191 offset:768
	ds_read_b32 v138, v191 offset:1024
	ds_read_b32 v139, v191 offset:1280
	ds_read_b32 v140, v191 offset:1536
	ds_read_b32 v141, v191 offset:1792
	ds_read_b32 v150, v191 offset:32768
	ds_read_b32 v151, v191 offset:33024
	ds_read_b32 v152, v191 offset:33280
	ds_read_b32 v153, v191 offset:33536
	ds_read_b32 v154, v191 offset:33792
	ds_read_b32 v155, v191 offset:34048
	s_waitcnt lgkmcnt(6)
	ds_read_b32 v142, v191 offset:2048
	ds_read_b32 v143, v191 offset:2304
	ds_read_b32 v144, v191 offset:2560
	ds_read_b32 v145, v191 offset:2816
	ds_read_b32 v146, v191 offset:3072
	ds_read_b32 v147, v191 offset:3328
	ds_read_b32 v148, v191 offset:3584
	ds_read_b32 v149, v191 offset:3840
	s_waitcnt lgkmcnt(6)
	ds_read_b32 v156, v191 offset:34304
	ds_read_b32 v157, v191 offset:34560
	ds_read_b32 v158, v191 offset:34816
	ds_read_b32 v159, v191 offset:35072
	ds_read_b32 v160, v191 offset:35328
	ds_read_b32 v161, v191 offset:35584
	ds_read_b32 v162, v191 offset:35840
	ds_read_b32 v163, v191 offset:36096
	s_waitcnt lgkmcnt(6)
	ds_read_b32 v164, v191 offset:36352
	ds_read_b32 v165, v191 offset:36608
	s_waitcnt lgkmcnt(0)
	v_mov_b32_e32 v48, v134
	v_mov_b32_e32 v49, v150
	v_fma_f32 v49, v135, v49, v151
	v_mul_f32_e32 v48, v48, v135
	v_fma_f32 v49, v136, v49, v152
	v_mul_f32_e32 v48, v48, v136
	v_fma_f32 v49, v137, v49, v153
	v_mul_f32_e32 v48, v48, v137
	v_fma_f32 v49, v138, v49, v154
	v_mul_f32_e32 v48, v48, v138
	v_fma_f32 v49, v139, v49, v155
	v_mul_f32_e32 v48, v48, v139
	v_fma_f32 v49, v140, v49, v156
	v_mul_f32_e32 v48, v48, v140
	v_fma_f32 v49, v141, v49, v157
	v_mul_f32_e32 v48, v48, v141
	v_fma_f32 v49, v142, v49, v158
	v_mul_f32_e32 v48, v48, v142
	v_fma_f32 v49, v143, v49, v159
	v_mul_f32_e32 v48, v48, v143
	v_fma_f32 v49, v144, v49, v160
	v_mul_f32_e32 v48, v48, v144
	v_fma_f32 v49, v145, v49, v161
	v_mul_f32_e32 v48, v48, v145
	v_fma_f32 v49, v146, v49, v162
	v_mul_f32_e32 v48, v48, v146
	v_fma_f32 v49, v147, v49, v163
	v_mul_f32_e32 v48, v48, v147
	v_fma_f32 v49, v148, v49, v164
	v_mul_f32_e32 v48, v48, v148
	v_fma_f32 v49, v149, v49, v165
	v_mul_f32_e32 v48, v48, v149
	ds_write_b64 v197, v[48:49]
	s_waitcnt vmcnt(16)
; #define LAS __attribute__((address_space(3)))
; __device__ __forceinline__ unsigned pk_bf16(float lo, float hi) { f32x2 v = {lo, hi}; bf16x2_t b = __builtin_convertvector(v, bf16x2_t); return __builtin_bit_cast(unsigned, b); }
; __device__ __forceinline__ void unpack8(u32x4 w, float* f) { f[0] = bf_lo(w.x); f[1] = bf_hi(w.x); f[2] = bf_lo(w.y); f[3] = bf_hi(w.y); f[4] = bf_lo(w.z); f[5] = bf_hi(w.z); f[6] = bf_lo(w.w); f[7] = bf_hi(w.w); }
; __device__ __forceinline__ void lru_unit_p(const P2Ctx& C, int b, int n, int half) {
;     ...
;         { float cw[4][8], cb8[8];
;           { const LAS float* cbp = CWL + 512 + cg * 8; const f32x4 c0 = *(const LAS f32x4*)cbp, c1 = *(const LAS f32x4*)(cbp + 4);
;             cb8[0] = c0[0]; cb8[1] = c0[1]; cb8[2] = c0[2]; cb8[3] = c0[3]; cb8[4] = c1[0]; cb8[5] = c1[1]; cb8[6] = c1[2]; cb8[7] = c1[3]; }
; #pragma unroll
;           for (int j = 0; j < 4; ++j) { const LAS float* cwp = CWL + j * 128 + cg * 8; const f32x4 c0 = *(const LAS f32x4*)cwp, c1 = *(const LAS f32x4*)(cwp + 4);
;               cw[j][0] = c0[0]; cw[j][1] = c0[1]; cw[j][2] = c0[2]; cw[j][3] = c0[3]; cw[j][4] = c1[0]; cw[j][5] = c1[1]; cw[j][6] = c1[2]; cw[j][7] = c1[3]; }
;           float x[7][8];
; #pragma unroll
;           for (int i = 0; i < 7; ++i) unpack8(rows[i], x[i]);
; #pragma unroll
;           for (int t = 0; t < 4; ++t) { float xc[8];
; #pragma unroll
;               for (int e = 0; e < 8; ++e) xc[e] = cb8[e];
; #pragma unroll
;               for (int j = 0; j < 4; ++j)
; #pragma unroll
;                   for (int e = 0; e < 8; ++e) xc[e] += cw[j][e] * x[t + j][e];
;               const int tok = run * 4 + t; u32x4 w; w.x = pk_bf16(xc[0], xc[1]); w.y = pk_bf16(xc[2], xc[3]); w.z = pk_bf16(xc[4], xc[5]); w.w = pk_bf16(xc[6], xc[7]);
;               *(LAS u32x4*)(XC + tok * 256 + ((cg ^ (tok & 15)) << 4)) = w; } }
.LlP_conv:
	ds_read_b64 v[48:49], v204 offset:0
	ds_read_b64 v[50:51], v204 offset:512
	ds_read_b64 v[52:53], v204 offset:1024
	ds_read_b64 v[54:55], v204 offset:1536
	ds_read_b64 v[56:57], v204 offset:2048
	v_lshlrev_b32_e32 v220, 16, v4
	v_and_b32_e32 v221, 0xffff0000, v4
	v_lshlrev_b32_e32 v222, 16, v8
	v_and_b32_e32 v223, 0xffff0000, v8
	v_lshlrev_b32_e32 v224, 16, v12
	v_and_b32_e32 v225, 0xffff0000, v12
	v_lshlrev_b32_e32 v226, 16, v16
	v_and_b32_e32 v227, 0xffff0000, v16
	v_lshlrev_b32_e32 v228, 16, v20
	v_and_b32_e32 v229, 0xffff0000, v20
	v_lshlrev_b32_e32 v230, 16, v24
	v_and_b32_e32 v231, 0xffff0000, v24
	v_lshlrev_b32_e32 v232, 16, v28
	v_and_b32_e32 v233, 0xffff0000, v28
	s_waitcnt lgkmcnt(0)
	v_fma_f32 v240, v48, v220, v56
	v_fmac_f32_e32 v240, v50, v222
	v_fmac_f32_e32 v240, v52, v224
	v_fmac_f32_e32 v240, v54, v226
	v_fma_f32 v241, v49, v221, v57
	v_fmac_f32_e32 v241, v51, v223
	v_fmac_f32_e32 v241, v53, v225
	v_fmac_f32_e32 v241, v55, v227
	v_fma_f32 v242, v48, v222, v56
	v_fmac_f32_e32 v242, v50, v224
	v_fmac_f32_e32 v242, v52, v226
	v_fmac_f32_e32 v242, v54, v228
	v_fma_f32 v243, v49, v223, v57
	v_fmac_f32_e32 v243, v51, v225
	v_fmac_f32_e32 v243, v53, v227
	v_fmac_f32_e32 v243, v55, v229
	v_fma_f32 v244, v48, v224, v56
	v_fmac_f32_e32 v244, v50, v226
	v_fmac_f32_e32 v244, v52, v228
	v_fmac_f32_e32 v244, v54, v230
	v_fma_f32 v245, v49, v225, v57
	v_fmac_f32_e32 v245, v51, v227
	v_fmac_f32_e32 v245, v53, v229
	v_fmac_f32_e32 v245, v55, v231
	v_fma_f32 v246, v48, v226, v56
	v_fmac_f32_e32 v246, v50, v228
	v_fmac_f32_e32 v246, v52, v230
	v_fmac_f32_e32 v246, v54, v232
	v_fma_f32 v247, v49, v227, v57
	v_fmac_f32_e32 v247, v51, v229
	v_fmac_f32_e32 v247, v53, v231
	v_fmac_f32_e32 v247, v55, v233
	v_cvt_pk_bf16_f32 v58, v240, v241
	v_cvt_pk_bf16_f32 v62, v242, v243
	v_cvt_pk_bf16_f32 v166, v244, v245
	v_cvt_pk_bf16_f32 v170, v246, v247
	ds_read_b64 v[48:49], v204 offset:8
	ds_read_b64 v[50:51], v204 offset:520
	ds_read_b64 v[52:53], v204 offset:1032
	ds_read_b64 v[54:55], v204 offset:1544
	ds_read_b64 v[56:57], v204 offset:2056
	v_lshlrev_b32_e32 v220, 16, v5
	v_and_b32_e32 v221, 0xffff0000, v5
	v_lshlrev_b32_e32 v222, 16, v9
	v_and_b32_e32 v223, 0xffff0000, v9
	v_lshlrev_b32_e32 v224, 16, v13
	v_and_b32_e32 v225, 0xffff0000, v13
	v_lshlrev_b32_e32 v226, 16, v17
	v_and_b32_e32 v227, 0xffff0000, v17
	v_lshlrev_b32_e32 v228, 16, v21
	v_and_b32_e32 v229, 0xffff0000, v21
	v_lshlrev_b32_e32 v230, 16, v25
	v_and_b32_e32 v231, 0xffff0000, v25
	v_lshlrev_b32_e32 v232, 16, v29
	v_and_b32_e32 v233, 0xffff0000, v29
	s_waitcnt lgkmcnt(0)
	v_fma_f32 v240, v48, v220, v56
	v_fmac_f32_e32 v240, v50, v222
	v_fmac_f32_e32 v240, v52, v224
	v_fmac_f32_e32 v240, v54, v226
	v_fma_f32 v241, v49, v221, v57
	v_fmac_f32_e32 v241, v51, v223
	v_fmac_f32_e32 v241, v53, v225
	v_fmac_f32_e32 v241, v55, v227
	v_fma_f32 v242, v48, v222, v56
	v_fmac_f32_e32 v242, v50, v224
	v_fmac_f32_e32 v242, v52, v226
	v_fmac_f32_e32 v242, v54, v228
	v_fma_f32 v243, v49, v223, v57
	v_fmac_f32_e32 v243, v51, v225
	v_fmac_f32_e32 v243, v53, v227
	v_fmac_f32_e32 v243, v55, v229
	v_fma_f32 v244, v48, v224, v56
	v_fmac_f32_e32 v244, v50, v226
	v_fmac_f32_e32 v244, v52, v228
	v_fmac_f32_e32 v244, v54, v230
	v_fma_f32 v245, v49, v225, v57
	v_fmac_f32_e32 v245, v51, v227
	v_fmac_f32_e32 v245, v53, v229
	v_fmac_f32_e32 v245, v55, v231
	v_fma_f32 v246, v48, v226, v56
	v_fmac_f32_e32 v246, v50, v228
	v_fmac_f32_e32 v246, v52, v230
	v_fmac_f32_e32 v246, v54, v232
	v_fma_f32 v247, v49, v227, v57
	v_fmac_f32_e32 v247, v51, v229
	v_fmac_f32_e32 v247, v53, v231
	v_fmac_f32_e32 v247, v55, v233
	v_cvt_pk_bf16_f32 v59, v240, v241
	v_cvt_pk_bf16_f32 v63, v242, v243
	v_cvt_pk_bf16_f32 v167, v244, v245
	v_cvt_pk_bf16_f32 v171, v246, v247
	ds_read_b64 v[48:49], v204 offset:16
	ds_read_b64 v[50:51], v204 offset:528
	ds_read_b64 v[52:53], v204 offset:1040
	ds_read_b64 v[54:55], v204 offset:1552
	ds_read_b64 v[56:57], v204 offset:2064
	v_lshlrev_b32_e32 v220, 16, v6
	v_and_b32_e32 v221, 0xffff0000, v6
	v_lshlrev_b32_e32 v222, 16, v10
	v_and_b32_e32 v223, 0xffff0000, v10
	v_lshlrev_b32_e32 v224, 16, v14
	v_and_b32_e32 v225, 0xffff0000, v14
	v_lshlrev_b32_e32 v226, 16, v18
	v_and_b32_e32 v227, 0xffff0000, v18
	v_lshlrev_b32_e32 v228, 16, v22
	v_and_b32_e32 v229, 0xffff0000, v22
	v_lshlrev_b32_e32 v230, 16, v26
	v_and_b32_e32 v231, 0xffff0000, v26
	v_lshlrev_b32_e32 v232, 16, v30
	v_and_b32_e32 v233, 0xffff0000, v30
	s_waitcnt lgkmcnt(0)
	v_fma_f32 v240, v48, v220, v56
	v_fmac_f32_e32 v240, v50, v222
	v_fmac_f32_e32 v240, v52, v224
	v_fmac_f32_e32 v240, v54, v226
	v_fma_f32 v241, v49, v221, v57
	v_fmac_f32_e32 v241, v51, v223
	v_fmac_f32_e32 v241, v53, v225
	v_fmac_f32_e32 v241, v55, v227
	v_fma_f32 v242, v48, v222, v56
	v_fmac_f32_e32 v242, v50, v224
	v_fmac_f32_e32 v242, v52, v226
	v_fmac_f32_e32 v242, v54, v228
	v_fma_f32 v243, v49, v223, v57
	v_fmac_f32_e32 v243, v51, v225
	v_fmac_f32_e32 v243, v53, v227
	v_fmac_f32_e32 v243, v55, v229
	v_fma_f32 v244, v48, v224, v56
	v_fmac_f32_e32 v244, v50, v226
	v_fmac_f32_e32 v244, v52, v228
	v_fmac_f32_e32 v244, v54, v230
	v_fma_f32 v245, v49, v225, v57
	v_fmac_f32_e32 v245, v51, v227
	v_fmac_f32_e32 v245, v53, v229
	v_fmac_f32_e32 v245, v55, v231
	v_fma_f32 v246, v48, v226, v56
	v_fmac_f32_e32 v246, v50, v228
	v_fmac_f32_e32 v246, v52, v230
	v_fmac_f32_e32 v246, v54, v232
	v_fma_f32 v247, v49, v227, v57
	v_fmac_f32_e32 v247, v51, v229
	v_fmac_f32_e32 v247, v53, v231
	v_fmac_f32_e32 v247, v55, v233
	v_cvt_pk_bf16_f32 v60, v240, v241
	v_cvt_pk_bf16_f32 v64, v242, v243
	v_cvt_pk_bf16_f32 v168, v244, v245
	v_cvt_pk_bf16_f32 v172, v246, v247
	ds_read_b64 v[48:49], v204 offset:24
	ds_read_b64 v[50:51], v204 offset:536
	ds_read_b64 v[52:53], v204 offset:1048
	ds_read_b64 v[54:55], v204 offset:1560
	ds_read_b64 v[56:57], v204 offset:2072
	v_lshlrev_b32_e32 v220, 16, v7
	v_and_b32_e32 v221, 0xffff0000, v7
	v_lshlrev_b32_e32 v222, 16, v11
	v_and_b32_e32 v223, 0xffff0000, v11
	v_lshlrev_b32_e32 v224, 16, v15
	v_and_b32_e32 v225, 0xffff0000, v15
	v_lshlrev_b32_e32 v226, 16, v19
	v_and_b32_e32 v227, 0xffff0000, v19
	v_lshlrev_b32_e32 v228, 16, v23
	v_and_b32_e32 v229, 0xffff0000, v23
	v_lshlrev_b32_e32 v230, 16, v27
	v_and_b32_e32 v231, 0xffff0000, v27
	v_lshlrev_b32_e32 v232, 16, v31
	v_and_b32_e32 v233, 0xffff0000, v31
	s_waitcnt lgkmcnt(0)
; #define LAS __attribute__((address_space(3)))
; __device__ __forceinline__ void lru_unit_p(const P2Ctx& C, int b, int n, int half) {
;     ...
;         if (ck + 1 < 16) { const int ttn = (ck + 1) * 128 + run * 4;
; #pragma unroll
;             for (int i = 0; i < 7; ++i) rown[i] = *(const u32x4*)(C.XB + (t0 + ttn - 3 + i) * DM + n * 128 + cg * 8); }
;         else {
; #pragma unroll
;             for (int i = 0; i < 7; ++i) rown[i] = (u32x4){0u, 0u, 0u, 0u}; }
;         bf16_t gg[16];
;         const size_t off0 = (t0 + ck * 128 + (tid >> 6) * 16) * DM + n * 128 + half * 64 + (tid & 63);
; #pragma unroll
;         for (int t = 0; t < 16; ++t) gg[t] = C.GG[off0 + (size_t)t * DM];
;         { float cw[4][8], cb8[8];
;           { const LAS float* cbp = CWL + 512 + cg * 8; const f32x4 c0 = *(const LAS f32x4*)cbp, c1 = *(const LAS f32x4*)(cbp + 4);
;             cb8[0] = c0[0]; cb8[1] = c0[1]; cb8[2] = c0[2]; cb8[3] = c0[3]; cb8[4] = c1[0]; cb8[5] = c1[1]; cb8[6] = c1[2]; cb8[7] = c1[3]; }
; #pragma unroll
;           for (int j = 0; j < 4; ++j) { const LAS float* cwp = CWL + j * 128 + cg * 8; const f32x4 c0 = *(const LAS f32x4*)cwp, c1 = *(const LAS f32x4*)(cwp + 4);
;               cw[j][0] = c0[0]; cw[j][1] = c0[1]; cw[j][2] = c0[2]; cw[j][3] = c0[3]; cw[j][4] = c1[0]; cw[j][5] = c1[1]; cw[j][6] = c1[2]; cw[j][7] = c1[3]; }
;           float x[7][8];
; #pragma unroll
;           for (int i = 0; i < 7; ++i) unpack8(rows[i], x[i]);
; #pragma unroll
;           for (int t = 0; t < 4; ++t) { float xc[8];
; #pragma unroll
;               for (int e = 0; e < 8; ++e) xc[e] = cb8[e];
; #pragma unroll
;               for (int j = 0; j < 4; ++j)
; #pragma unroll
;                   for (int e = 0; e < 8; ++e) xc[e] += cw[j][e] * x[t + j][e];
;               const int tok = run * 4 + t; u32x4 w; w.x = pk_bf16(xc[0], xc[1]); w.y = pk_bf16(xc[2], xc[3]); w.z = pk_bf16(xc[4], xc[5]); w.w = pk_bf16(xc[6], xc[7]);
;               *(LAS u32x4*)(XC + tok * 256 + ((cg ^ (tok & 15)) << 4)) = w; } }
;         __builtin_amdgcn_sched_barrier(0);
;         __syncthreads();
;         f32x16 da, dx;
; #pragma unroll
;         for (int r = 0; r < 16; ++r) { da[r] = 0.f; dx[r] = 0.f; }
;         { const int tokA = tkb * 32 + r32;
; #pragma unroll
;           for (int ks = 0; ks < 8; ++ks) { const bf16x8 xf = *(const LAS bf16x8*)(XC + tokA * 256 + (((2 * ks + hi) ^ (tokA & 15)) << 4));
	v_fma_f32 v240, v48, v220, v56
	v_fmac_f32_e32 v240, v50, v222
	v_fmac_f32_e32 v240, v52, v224
	v_fmac_f32_e32 v240, v54, v226
	v_fma_f32 v241, v49, v221, v57
	v_fmac_f32_e32 v241, v51, v223
	v_fmac_f32_e32 v241, v53, v225
	v_fmac_f32_e32 v241, v55, v227
	v_fma_f32 v242, v48, v222, v56
	v_fmac_f32_e32 v242, v50, v224
	v_fmac_f32_e32 v242, v52, v226
	v_fmac_f32_e32 v242, v54, v228
	v_fma_f32 v243, v49, v223, v57
	v_fmac_f32_e32 v243, v51, v225
	v_fmac_f32_e32 v243, v53, v227
	v_fmac_f32_e32 v243, v55, v229
	v_fma_f32 v244, v48, v224, v56
	v_fmac_f32_e32 v244, v50, v226
	v_fmac_f32_e32 v244, v52, v228
	v_fmac_f32_e32 v244, v54, v230
	v_fma_f32 v245, v49, v225, v57
	v_fmac_f32_e32 v245, v51, v227
	v_fmac_f32_e32 v245, v53, v229
	v_fmac_f32_e32 v245, v55, v231
	v_fma_f32 v246, v48, v226, v56
	v_fmac_f32_e32 v246, v50, v228
	v_fmac_f32_e32 v246, v52, v230
	v_fmac_f32_e32 v246, v54, v232
	v_fma_f32 v247, v49, v227, v57
	v_fmac_f32_e32 v247, v51, v229
	v_fmac_f32_e32 v247, v53, v231
	v_fmac_f32_e32 v247, v55, v233
	v_cvt_pk_bf16_f32 v61, v240, v241
	v_cvt_pk_bf16_f32 v65, v242, v243
	v_cvt_pk_bf16_f32 v169, v244, v245
	v_cvt_pk_bf16_f32 v173, v246, v247
	ds_write_b128 v192, v[58:61]
	ds_write_b128 v193, v[62:65]
	ds_write_b128 v194, v[166:169]
	ds_write_b128 v195, v[170:173]
	s_add_i32 s22, s20, 2
	s_min_u32 s12, s22, 15
	s_lshl_b32 s12, s12, 18
	s_add_u32 s10, s14, s12
	s_addc_u32 s11, s15, 0
	global_load_dwordx4 v[4:7], v200, s[10:11] offset:-4096
	global_load_dwordx4 v[8:11], v200, s[10:11] offset:-2048
	global_load_dwordx4 v[12:15], v200, s[10:11] offset:0
	global_load_dwordx4 v[16:19], v200, s[10:11] offset:2048
	global_load_dwordx4 v[20:23], v201, s[10:11] offset:-2048
	global_load_dwordx4 v[24:27], v201, s[10:11] offset:0
	global_load_dwordx4 v[28:31], v201, s[10:11] offset:2048
	s_waitcnt lgkmcnt(0)
	s_barrier
	s_cmp_lt_i32 s20, 0
	s_cbranch_scc1 .LlP_gg
	ds_read_b32 v234, v203
	ds_read_b64 v[220:221], v198 offset:0
	ds_read_b64 v[222:223], v198 offset:512
	ds_read_b64 v[224:225], v198 offset:1024
	ds_read_b64 v[226:227], v198 offset:1536
	ds_read_b64 v[228:229], v198 offset:2048
	ds_read_b64 v[230:231], v198 offset:2560
	ds_read_b64 v[232:233], v198 offset:3072
	s_waitcnt lgkmcnt(0)
	v_mov_b32_e32 v240, v234
	s_cmp_gt_u32 s21, 0
	s_cbranch_scc0 .LlP_hin_done_2
	v_fma_f32 v240, v220, v240, v221
	s_cmp_gt_u32 s21, 1
	s_cbranch_scc0 .LlP_hin_done_2
	v_fma_f32 v240, v222, v240, v223
	s_cmp_gt_u32 s21, 2
	s_cbranch_scc0 .LlP_hin_done_2
	v_fma_f32 v240, v224, v240, v225
	s_cmp_gt_u32 s21, 3
	s_cbranch_scc0 .LlP_hin_done_2
	v_fma_f32 v240, v226, v240, v227
	s_cmp_gt_u32 s21, 4
	s_cbranch_scc0 .LlP_hin_done_2
	v_fma_f32 v240, v228, v240, v229
	s_cmp_gt_u32 s21, 5
	s_cbranch_scc0 .LlP_hin_done_2
	v_fma_f32 v240, v230, v240, v231
	s_cmp_gt_u32 s21, 6
	s_cbranch_scc0 .LlP_hin_done_2
	v_fma_f32 v240, v232, v240, v233
; __device__ __forceinline__ unsigned pk_bf16(float lo, float hi) { f32x2 v = {lo, hi}; bf16x2_t b = __builtin_convertvector(v, bf16x2_t); return __builtin_bit_cast(unsigned, b); }
; __device__ __forceinline__ float bf2f(bf16_t v) { return __uint_as_float(((unsigned)v) << 16); }
; __device__ __forceinline__ void lru_unit_p(const P2Ctx& C, int b, int n, int half) {
;     ...
;         const size_t off0 = (t0 + ck * 128 + (tid >> 6) * 16) * DM + n * 128 + half * 64 + (tid & 63);
; #pragma unroll
;         for (int t = 0; t < 16; ++t) gg[t] = C.GG[off0 + (size_t)t * DM];
;     ...
;           float hin = CAR[c];
;           for (int s = 0; s < seg; ++s) hin = SEG[(s * 64 + c) * 2] * hin + SEG[(s * 64 + c) * 2 + 1];
;           float hv = hin;
; #pragma unroll
;           for (int t = 0; t < 16; ++t) { const int tok = seg * 16 + t; const float av = AA[tok * 64 + c], uv = UU[tok * 64 + c]; hv = av * hv + uv;
;               C.BO[off0 + (size_t)t * DM] = (bf16_t)(pk_bf16(hv * bf2f(gg[t]), 0.f) & 0xffffu); }
;           __syncthreads();
;           if (seg == 7) CAR[c] = hv; }
; #pragma unroll
;         for (int i = 0; i < 7; ++i) rows[i] = rown[i];
.LlP_hin_done_2:
	s_waitcnt vmcnt(7)
	s_min_u32 s12, s20, 15
	s_lshl_b32 s12, s12, 18
	s_add_u32 s10, s18, s12
	s_addc_u32 s11, s19, 0
	v_fma_f32 v240, v134, v240, v150
	v_lshlrev_b32_e32 v241, 16, v32
	v_mul_f32_e32 v241, v240, v241
	v_cvt_pk_bf16_f32 v242, v241, v241
	global_store_short v202, v242, s[10:11]
	v_fma_f32 v240, v135, v240, v151
	v_lshlrev_b32_e32 v241, 16, v33
	v_mul_f32_e32 v241, v240, v241
	v_cvt_pk_bf16_f32 v243, v241, v241
	global_store_short v202, v243, s[10:11] offset:2048
	s_add_u32 s10, s10, 0x1000
	s_addc_u32 s11, s11, 0
	v_fma_f32 v240, v136, v240, v152
	v_lshlrev_b32_e32 v241, 16, v34
	v_mul_f32_e32 v241, v240, v241
	v_cvt_pk_bf16_f32 v242, v241, v241
	global_store_short v202, v242, s[10:11]
	v_fma_f32 v240, v137, v240, v153
	v_lshlrev_b32_e32 v241, 16, v35
	v_mul_f32_e32 v241, v240, v241
	v_cvt_pk_bf16_f32 v243, v241, v241
	global_store_short v202, v243, s[10:11] offset:2048
	s_add_u32 s10, s10, 0x1000
	s_addc_u32 s11, s11, 0
	v_fma_f32 v240, v138, v240, v154
	v_lshlrev_b32_e32 v241, 16, v36
	v_mul_f32_e32 v241, v240, v241
	v_cvt_pk_bf16_f32 v242, v241, v241
	global_store_short v202, v242, s[10:11]
	v_fma_f32 v240, v139, v240, v155
	v_lshlrev_b32_e32 v241, 16, v37
	v_mul_f32_e32 v241, v240, v241
	v_cvt_pk_bf16_f32 v243, v241, v241
	global_store_short v202, v243, s[10:11] offset:2048
	s_add_u32 s10, s10, 0x1000
	s_addc_u32 s11, s11, 0
	v_fma_f32 v240, v140, v240, v156
	v_lshlrev_b32_e32 v241, 16, v38
	v_mul_f32_e32 v241, v240, v241
	v_cvt_pk_bf16_f32 v242, v241, v241
	global_store_short v202, v242, s[10:11]
	v_fma_f32 v240, v141, v240, v157
	v_lshlrev_b32_e32 v241, 16, v39
	v_mul_f32_e32 v241, v240, v241
	v_cvt_pk_bf16_f32 v243, v241, v241
	global_store_short v202, v243, s[10:11] offset:2048
	s_add_u32 s10, s10, 0x1000
	s_addc_u32 s11, s11, 0
	v_fma_f32 v240, v142, v240, v158
	v_lshlrev_b32_e32 v241, 16, v40
	v_mul_f32_e32 v241, v240, v241
	v_cvt_pk_bf16_f32 v242, v241, v241
	global_store_short v202, v242, s[10:11]
	v_fma_f32 v240, v143, v240, v159
	v_lshlrev_b32_e32 v241, 16, v41
	v_mul_f32_e32 v241, v240, v241
	v_cvt_pk_bf16_f32 v243, v241, v241
	global_store_short v202, v243, s[10:11] offset:2048
	s_add_u32 s10, s10, 0x1000
	s_addc_u32 s11, s11, 0
	v_fma_f32 v240, v144, v240, v160
	v_lshlrev_b32_e32 v241, 16, v42
	v_mul_f32_e32 v241, v240, v241
	v_cvt_pk_bf16_f32 v242, v241, v241
	global_store_short v202, v242, s[10:11]
	v_fma_f32 v240, v145, v240, v161
	v_lshlrev_b32_e32 v241, 16, v43
	v_mul_f32_e32 v241, v240, v241
	v_cvt_pk_bf16_f32 v243, v241, v241
	global_store_short v202, v243, s[10:11] offset:2048
	s_add_u32 s10, s10, 0x1000
	s_addc_u32 s11, s11, 0
	v_fma_f32 v240, v146, v240, v162
	v_lshlrev_b32_e32 v241, 16, v44
	v_mul_f32_e32 v241, v240, v241
	v_cvt_pk_bf16_f32 v242, v241, v241
	global_store_short v202, v242, s[10:11]
	v_fma_f32 v240, v147, v240, v163
	v_lshlrev_b32_e32 v241, 16, v45
	v_mul_f32_e32 v241, v240, v241
	v_cvt_pk_bf16_f32 v243, v241, v241
	global_store_short v202, v243, s[10:11] offset:2048
	s_add_u32 s10, s10, 0x1000
	s_addc_u32 s11, s11, 0
	v_fma_f32 v240, v148, v240, v164
	v_lshlrev_b32_e32 v241, 16, v46
	v_mul_f32_e32 v241, v240, v241
	v_cvt_pk_bf16_f32 v242, v241, v241
	global_store_short v202, v242, s[10:11]
	v_fma_f32 v240, v149, v240, v165
	v_lshlrev_b32_e32 v241, 16, v47
	v_mul_f32_e32 v241, v240, v241
	v_cvt_pk_bf16_f32 v243, v241, v241
	global_store_short v202, v243, s[10:11] offset:2048
	v_xor_b32_e32 v203, 0xb00, v203
	s_cmp_eq_u32 s21, 7
	s_cbranch_scc0 .LlP_nocar_3
	ds_write_b32 v203, v240
.LlP_nocar_3:
.LlP_gg:
	s_add_i32 s22, s20, 1
	s_min_u32 s12, s22, 15
	s_lshl_b32 s12, s12, 18
	s_add_u32 s10, s16, s12
	s_addc_u32 s11, s17, 0
	global_load_ushort v32, v202, s[10:11]
	global_load_ushort v33, v202, s[10:11] offset:2048
	s_add_u32 s10, s10, 0x1000
	s_addc_u32 s11, s11, 0
	global_load_ushort v34, v202, s[10:11]
	global_load_ushort v35, v202, s[10:11] offset:2048
	s_add_u32 s10, s10, 0x1000
	s_addc_u32 s11, s11, 0
	global_load_ushort v36, v202, s[10:11]
	global_load_ushort v37, v202, s[10:11] offset:2048
	s_add_u32 s10, s10, 0x1000
	s_addc_u32 s11, s11, 0
	global_load_ushort v38, v202, s[10:11]
	global_load_ushort v39, v202, s[10:11] offset:2048
	s_add_u32 s10, s10, 0x1000
	s_addc_u32 s11, s11, 0
	global_load_ushort v40, v202, s[10:11]
	global_load_ushort v41, v202, s[10:11] offset:2048
	s_add_u32 s10, s10, 0x1000
	s_addc_u32 s11, s11, 0
	global_load_ushort v42, v202, s[10:11]
	global_load_ushort v43, v202, s[10:11] offset:2048
	s_add_u32 s10, s10, 0x1000
	s_addc_u32 s11, s11, 0
	global_load_ushort v44, v202, s[10:11]
	global_load_ushort v45, v202, s[10:11] offset:2048
	s_add_u32 s10, s10, 0x1000
	s_addc_u32 s11, s11, 0
	global_load_ushort v46, v202, s[10:11]
	global_load_ushort v47, v202, s[10:11] offset:2048
	s_add_i32 s20, s20, 1
	s_cmp_lt_i32 s20, 16
	s_cbranch_scc1 .LlP_loop
	s_waitcnt vmcnt(0) lgkmcnt(0)
